# M1 row-major epilogue with stores issued every ~24 VALU (two rows at a time) instead of bursts of four
# speedup vs baseline: 1.0053x; 1.0053x over previous
.LBB0_958:
	v_bfe_u32 v192, v0, 4, 2
	v_and_b32_e32 v193, 3, v0
	v_lshl_or_b32 v194, v192, 2, v193
	v_lshlrev_b32_e32 v194, 2, v194
	ds_bpermute_b32 v176, v194, v140
	ds_bpermute_b32 v177, v194, v144
	ds_bpermute_b32 v178, v194, v148
	ds_bpermute_b32 v179, v194, v150
	ds_bpermute_b32 v180, v194, v136
	ds_bpermute_b32 v181, v194, v137
	ds_bpermute_b32 v182, v194, v152
	ds_bpermute_b32 v183, v194, v154
	v_lshlrev_b32_e32 v193, 2, v192
	v_and_b32_e32 v175, -16, v146
	v_add_u32_e32 v175, v175, v193
	v_lshlrev_b32_e32 v175, 13, v175
	v_and_b32_e32 v193, 15, v0
	v_lshlrev_b32_e32 v193, 3, v193
	v_lshrrev_b32_e32 v192, 5, v226
	v_lshl_or_b32 v193, v192, 6, v193
	v_lshl_or_b32 v193, s59, 9, v193
	v_or_b32_e32 v175, v175, v193
	s_waitcnt lgkmcnt(7)
	v_mov_b32_dpp v184, v176 quad_perm:[0,0,0,0] row_mask:0xf bank_mask:0xf
	v_mov_b32_dpp v185, v176 quad_perm:[1,1,1,1] row_mask:0xf bank_mask:0xf
	v_mov_b32_dpp v186, v176 quad_perm:[2,2,2,2] row_mask:0xf bank_mask:0xf
	v_mov_b32_dpp v187, v176 quad_perm:[3,3,3,3] row_mask:0xf bank_mask:0xf
	v_pk_mul_f32 v[130:131], v[130:131], v[184:185]
	v_pk_mul_f32 v[126:127], v[126:127], v[184:185]
	v_pk_mul_f32 v[122:123], v[122:123], v[184:185]
	v_pk_mul_f32 v[118:119], v[118:119], v[184:185]
	v_max_f32_e32 v130, 0, v130
	v_max_f32_e32 v131, 0, v131
	v_max_f32_e32 v126, 0, v126
	v_max_f32_e32 v127, 0, v127
	v_max_f32_e32 v122, 0, v122
	v_max_f32_e32 v123, 0, v123
	v_max_f32_e32 v118, 0, v118
	v_max_f32_e32 v119, 0, v119
	v_pk_mul_f32 v[130:131], v[130:131], v[130:131]
	v_pk_mul_f32 v[126:127], v[126:127], v[126:127]
	v_pk_mul_f32 v[122:123], v[122:123], v[122:123]
	v_pk_mul_f32 v[118:119], v[118:119], v[118:119]
	v_cvt_pk_bf16_f32 v188, v130, v126
	v_cvt_pk_bf16_f32 v189, v122, v118
	global_store_dwordx2 v175, v[188:189], s[4:5] sc1
	v_cvt_pk_bf16_f32 v190, v131, v127
	v_cvt_pk_bf16_f32 v191, v123, v119
	v_add_u32_e32 v192, 0x2000, v175
	global_store_dwordx2 v192, v[190:191], s[4:5] sc1
	v_pk_mul_f32 v[132:133], v[132:133], v[186:187]
	v_pk_mul_f32 v[128:129], v[128:129], v[186:187]
	v_pk_mul_f32 v[124:125], v[124:125], v[186:187]
	v_pk_mul_f32 v[120:121], v[120:121], v[186:187]
	v_max_f32_e32 v132, 0, v132
	v_max_f32_e32 v133, 0, v133
	v_max_f32_e32 v128, 0, v128
	v_max_f32_e32 v129, 0, v129
	v_max_f32_e32 v124, 0, v124
	v_max_f32_e32 v125, 0, v125
	v_max_f32_e32 v120, 0, v120
	v_max_f32_e32 v121, 0, v121
	v_pk_mul_f32 v[132:133], v[132:133], v[132:133]
	v_pk_mul_f32 v[128:129], v[128:129], v[128:129]
	v_pk_mul_f32 v[124:125], v[124:125], v[124:125]
	v_pk_mul_f32 v[120:121], v[120:121], v[120:121]
	v_cvt_pk_bf16_f32 v194, v132, v128
	v_cvt_pk_bf16_f32 v195, v124, v120
	v_add_u32_e32 v193, 0x4000, v175
	global_store_dwordx2 v193, v[194:195], s[4:5] sc1
	v_cvt_pk_bf16_f32 v196, v133, v129
	v_cvt_pk_bf16_f32 v197, v125, v121
	v_add_u32_e32 v2, 0x6000, v175
	global_store_dwordx2 v2, v[196:197], s[4:5] sc1
	s_waitcnt lgkmcnt(6)
	v_mov_b32_dpp v184, v177 quad_perm:[0,0,0,0] row_mask:0xf bank_mask:0xf
	v_mov_b32_dpp v185, v177 quad_perm:[1,1,1,1] row_mask:0xf bank_mask:0xf
	v_mov_b32_dpp v186, v177 quad_perm:[2,2,2,2] row_mask:0xf bank_mask:0xf
	v_mov_b32_dpp v187, v177 quad_perm:[3,3,3,3] row_mask:0xf bank_mask:0xf
	v_pk_mul_f32 v[114:115], v[114:115], v[184:185]
	v_pk_mul_f32 v[110:111], v[110:111], v[184:185]
	v_pk_mul_f32 v[106:107], v[106:107], v[184:185]
	v_pk_mul_f32 v[102:103], v[102:103], v[184:185]
	v_max_f32_e32 v114, 0, v114
	v_max_f32_e32 v115, 0, v115
	v_max_f32_e32 v110, 0, v110
	v_max_f32_e32 v111, 0, v111
	v_max_f32_e32 v106, 0, v106
	v_max_f32_e32 v107, 0, v107
	v_max_f32_e32 v102, 0, v102
	v_max_f32_e32 v103, 0, v103
	v_pk_mul_f32 v[114:115], v[114:115], v[114:115]
	v_pk_mul_f32 v[110:111], v[110:111], v[110:111]
	v_pk_mul_f32 v[106:107], v[106:107], v[106:107]
	v_pk_mul_f32 v[102:103], v[102:103], v[102:103]
	v_cvt_pk_bf16_f32 v188, v114, v110
	v_cvt_pk_bf16_f32 v189, v106, v102
	v_add_u32_e32 v3, 0x20000, v175
	global_store_dwordx2 v3, v[188:189], s[4:5] sc1
	v_cvt_pk_bf16_f32 v190, v115, v111
	v_cvt_pk_bf16_f32 v191, v107, v103
	v_add_u32_e32 v192, 0x22000, v175
	global_store_dwordx2 v192, v[190:191], s[4:5] sc1
	v_pk_mul_f32 v[116:117], v[116:117], v[186:187]
	v_pk_mul_f32 v[112:113], v[112:113], v[186:187]
	v_pk_mul_f32 v[108:109], v[108:109], v[186:187]
	v_pk_mul_f32 v[104:105], v[104:105], v[186:187]
	v_max_f32_e32 v116, 0, v116
	v_max_f32_e32 v117, 0, v117
	v_max_f32_e32 v112, 0, v112
	v_max_f32_e32 v113, 0, v113
	v_max_f32_e32 v108, 0, v108
	v_max_f32_e32 v109, 0, v109
	v_max_f32_e32 v104, 0, v104
	v_max_f32_e32 v105, 0, v105
	v_pk_mul_f32 v[116:117], v[116:117], v[116:117]
	v_pk_mul_f32 v[112:113], v[112:113], v[112:113]
	v_pk_mul_f32 v[108:109], v[108:109], v[108:109]
	v_pk_mul_f32 v[104:105], v[104:105], v[104:105]
	v_cvt_pk_bf16_f32 v194, v116, v112
	v_cvt_pk_bf16_f32 v195, v108, v104
	v_add_u32_e32 v193, 0x24000, v175
	global_store_dwordx2 v193, v[194:195], s[4:5] sc1
	v_cvt_pk_bf16_f32 v196, v117, v113
	v_cvt_pk_bf16_f32 v197, v109, v105
	v_add_u32_e32 v2, 0x26000, v175
	global_store_dwordx2 v2, v[196:197], s[4:5] sc1
	s_waitcnt lgkmcnt(5)
	v_mov_b32_dpp v184, v178 quad_perm:[0,0,0,0] row_mask:0xf bank_mask:0xf
	v_mov_b32_dpp v185, v178 quad_perm:[1,1,1,1] row_mask:0xf bank_mask:0xf
	v_mov_b32_dpp v186, v178 quad_perm:[2,2,2,2] row_mask:0xf bank_mask:0xf
	v_mov_b32_dpp v187, v178 quad_perm:[3,3,3,3] row_mask:0xf bank_mask:0xf
	v_pk_mul_f32 v[98:99], v[98:99], v[184:185]
	v_pk_mul_f32 v[94:95], v[94:95], v[184:185]
	v_pk_mul_f32 v[90:91], v[90:91], v[184:185]
	v_pk_mul_f32 v[86:87], v[86:87], v[184:185]
	v_max_f32_e32 v98, 0, v98
	v_max_f32_e32 v99, 0, v99
	v_max_f32_e32 v94, 0, v94
	v_max_f32_e32 v95, 0, v95
	v_max_f32_e32 v90, 0, v90
	v_max_f32_e32 v91, 0, v91
	v_max_f32_e32 v86, 0, v86
	v_max_f32_e32 v87, 0, v87
	v_pk_mul_f32 v[98:99], v[98:99], v[98:99]
	v_pk_mul_f32 v[94:95], v[94:95], v[94:95]
	v_pk_mul_f32 v[90:91], v[90:91], v[90:91]
	v_pk_mul_f32 v[86:87], v[86:87], v[86:87]
	v_cvt_pk_bf16_f32 v188, v98, v94
	v_cvt_pk_bf16_f32 v189, v90, v86
	v_add_u32_e32 v3, 0x40000, v175
	global_store_dwordx2 v3, v[188:189], s[4:5] sc1
	v_cvt_pk_bf16_f32 v190, v99, v95
	v_cvt_pk_bf16_f32 v191, v91, v87
	v_add_u32_e32 v192, 0x42000, v175
	global_store_dwordx2 v192, v[190:191], s[4:5] sc1
	v_pk_mul_f32 v[100:101], v[100:101], v[186:187]
	v_pk_mul_f32 v[96:97], v[96:97], v[186:187]
	v_pk_mul_f32 v[92:93], v[92:93], v[186:187]
	v_pk_mul_f32 v[88:89], v[88:89], v[186:187]
	v_max_f32_e32 v100, 0, v100
	v_max_f32_e32 v101, 0, v101
	v_max_f32_e32 v96, 0, v96
	v_max_f32_e32 v97, 0, v97
	v_max_f32_e32 v92, 0, v92
	v_max_f32_e32 v93, 0, v93
	v_max_f32_e32 v88, 0, v88
	v_max_f32_e32 v89, 0, v89
	v_pk_mul_f32 v[100:101], v[100:101], v[100:101]
	v_pk_mul_f32 v[96:97], v[96:97], v[96:97]
	v_pk_mul_f32 v[92:93], v[92:93], v[92:93]
	v_pk_mul_f32 v[88:89], v[88:89], v[88:89]
	v_cvt_pk_bf16_f32 v194, v100, v96
	v_cvt_pk_bf16_f32 v195, v92, v88
	v_add_u32_e32 v193, 0x44000, v175
	global_store_dwordx2 v193, v[194:195], s[4:5] sc1
	v_cvt_pk_bf16_f32 v196, v101, v97
	v_cvt_pk_bf16_f32 v197, v93, v89
	v_add_u32_e32 v2, 0x46000, v175
	global_store_dwordx2 v2, v[196:197], s[4:5] sc1
	s_waitcnt lgkmcnt(4)
	v_mov_b32_dpp v184, v179 quad_perm:[0,0,0,0] row_mask:0xf bank_mask:0xf
	v_mov_b32_dpp v185, v179 quad_perm:[1,1,1,1] row_mask:0xf bank_mask:0xf
	v_mov_b32_dpp v186, v179 quad_perm:[2,2,2,2] row_mask:0xf bank_mask:0xf
	v_mov_b32_dpp v187, v179 quad_perm:[3,3,3,3] row_mask:0xf bank_mask:0xf
	v_pk_mul_f32 v[82:83], v[82:83], v[184:185]
	v_pk_mul_f32 v[78:79], v[78:79], v[184:185]
	v_pk_mul_f32 v[74:75], v[74:75], v[184:185]
	v_pk_mul_f32 v[70:71], v[70:71], v[184:185]
	v_max_f32_e32 v82, 0, v82
	v_max_f32_e32 v83, 0, v83
	v_max_f32_e32 v78, 0, v78
	v_max_f32_e32 v79, 0, v79
	v_max_f32_e32 v74, 0, v74
	v_max_f32_e32 v75, 0, v75
	v_max_f32_e32 v70, 0, v70
	v_max_f32_e32 v71, 0, v71
	v_pk_mul_f32 v[82:83], v[82:83], v[82:83]
	v_pk_mul_f32 v[78:79], v[78:79], v[78:79]
	v_pk_mul_f32 v[74:75], v[74:75], v[74:75]
	v_pk_mul_f32 v[70:71], v[70:71], v[70:71]
	v_cvt_pk_bf16_f32 v188, v82, v78
	v_cvt_pk_bf16_f32 v189, v74, v70
	v_add_u32_e32 v3, 0x60000, v175
	global_store_dwordx2 v3, v[188:189], s[4:5] sc1
	v_cvt_pk_bf16_f32 v190, v83, v79
	v_cvt_pk_bf16_f32 v191, v75, v71
	v_add_u32_e32 v192, 0x62000, v175
	global_store_dwordx2 v192, v[190:191], s[4:5] sc1
	v_pk_mul_f32 v[84:85], v[84:85], v[186:187]
	v_pk_mul_f32 v[80:81], v[80:81], v[186:187]
	v_pk_mul_f32 v[76:77], v[76:77], v[186:187]
	v_pk_mul_f32 v[72:73], v[72:73], v[186:187]
	v_max_f32_e32 v84, 0, v84
	v_max_f32_e32 v85, 0, v85
	v_max_f32_e32 v80, 0, v80
	v_max_f32_e32 v81, 0, v81
	v_max_f32_e32 v76, 0, v76
	v_max_f32_e32 v77, 0, v77
	v_max_f32_e32 v72, 0, v72
	v_max_f32_e32 v73, 0, v73
	v_pk_mul_f32 v[84:85], v[84:85], v[84:85]
	v_pk_mul_f32 v[80:81], v[80:81], v[80:81]
	v_pk_mul_f32 v[76:77], v[76:77], v[76:77]
	v_pk_mul_f32 v[72:73], v[72:73], v[72:73]
	v_cvt_pk_bf16_f32 v194, v84, v80
	v_cvt_pk_bf16_f32 v195, v76, v72
	v_add_u32_e32 v193, 0x64000, v175
	global_store_dwordx2 v193, v[194:195], s[4:5] sc1
	v_cvt_pk_bf16_f32 v196, v85, v81
	v_cvt_pk_bf16_f32 v197, v77, v73
	v_add_u32_e32 v2, 0x66000, v175
	global_store_dwordx2 v2, v[196:197], s[4:5] sc1
	s_waitcnt lgkmcnt(3)
	v_mov_b32_dpp v184, v180 quad_perm:[0,0,0,0] row_mask:0xf bank_mask:0xf
	v_mov_b32_dpp v185, v180 quad_perm:[1,1,1,1] row_mask:0xf bank_mask:0xf
	v_mov_b32_dpp v186, v180 quad_perm:[2,2,2,2] row_mask:0xf bank_mask:0xf
	v_mov_b32_dpp v187, v180 quad_perm:[3,3,3,3] row_mask:0xf bank_mask:0xf
	v_pk_mul_f32 v[66:67], v[66:67], v[184:185]
	v_pk_mul_f32 v[62:63], v[62:63], v[184:185]
	v_pk_mul_f32 v[58:59], v[58:59], v[184:185]
	v_pk_mul_f32 v[54:55], v[54:55], v[184:185]
	v_max_f32_e32 v66, 0, v66
	v_max_f32_e32 v67, 0, v67
	v_max_f32_e32 v62, 0, v62
	v_max_f32_e32 v63, 0, v63
	v_max_f32_e32 v58, 0, v58
	v_max_f32_e32 v59, 0, v59
	v_max_f32_e32 v54, 0, v54
	v_max_f32_e32 v55, 0, v55
	v_pk_mul_f32 v[66:67], v[66:67], v[66:67]
	v_pk_mul_f32 v[62:63], v[62:63], v[62:63]
	v_pk_mul_f32 v[58:59], v[58:59], v[58:59]
	v_pk_mul_f32 v[54:55], v[54:55], v[54:55]
	v_cvt_pk_bf16_f32 v188, v66, v62
	v_cvt_pk_bf16_f32 v189, v58, v54
	v_add_u32_e32 v3, 0x100000, v175
	global_store_dwordx2 v3, v[188:189], s[4:5] sc1
	v_cvt_pk_bf16_f32 v190, v67, v63
	v_cvt_pk_bf16_f32 v191, v59, v55
	v_add_u32_e32 v192, 0x102000, v175
	global_store_dwordx2 v192, v[190:191], s[4:5] sc1
	v_pk_mul_f32 v[68:69], v[68:69], v[186:187]
	v_pk_mul_f32 v[64:65], v[64:65], v[186:187]
	v_pk_mul_f32 v[60:61], v[60:61], v[186:187]
	v_pk_mul_f32 v[56:57], v[56:57], v[186:187]
	v_max_f32_e32 v68, 0, v68
	v_max_f32_e32 v69, 0, v69
	v_max_f32_e32 v64, 0, v64
	v_max_f32_e32 v65, 0, v65
	v_max_f32_e32 v60, 0, v60
	v_max_f32_e32 v61, 0, v61
	v_max_f32_e32 v56, 0, v56
	v_max_f32_e32 v57, 0, v57
	v_pk_mul_f32 v[68:69], v[68:69], v[68:69]
	v_pk_mul_f32 v[64:65], v[64:65], v[64:65]
	v_pk_mul_f32 v[60:61], v[60:61], v[60:61]
	v_pk_mul_f32 v[56:57], v[56:57], v[56:57]
	v_cvt_pk_bf16_f32 v194, v68, v64
	v_cvt_pk_bf16_f32 v195, v60, v56
	v_add_u32_e32 v193, 0x104000, v175
	global_store_dwordx2 v193, v[194:195], s[4:5] sc1
	v_cvt_pk_bf16_f32 v196, v69, v65
	v_cvt_pk_bf16_f32 v197, v61, v57
	v_add_u32_e32 v2, 0x106000, v175
	global_store_dwordx2 v2, v[196:197], s[4:5] sc1
	s_waitcnt lgkmcnt(2)
	v_mov_b32_dpp v184, v181 quad_perm:[0,0,0,0] row_mask:0xf bank_mask:0xf
	v_mov_b32_dpp v185, v181 quad_perm:[1,1,1,1] row_mask:0xf bank_mask:0xf
	v_mov_b32_dpp v186, v181 quad_perm:[2,2,2,2] row_mask:0xf bank_mask:0xf
	v_mov_b32_dpp v187, v181 quad_perm:[3,3,3,3] row_mask:0xf bank_mask:0xf
	v_pk_mul_f32 v[50:51], v[50:51], v[184:185]
	v_pk_mul_f32 v[46:47], v[46:47], v[184:185]
	v_pk_mul_f32 v[42:43], v[42:43], v[184:185]
	v_pk_mul_f32 v[38:39], v[38:39], v[184:185]
	v_max_f32_e32 v50, 0, v50
	v_max_f32_e32 v51, 0, v51
	v_max_f32_e32 v46, 0, v46
	v_max_f32_e32 v47, 0, v47
	v_max_f32_e32 v42, 0, v42
	v_max_f32_e32 v43, 0, v43
	v_max_f32_e32 v38, 0, v38
	v_max_f32_e32 v39, 0, v39
	v_pk_mul_f32 v[50:51], v[50:51], v[50:51]
	v_pk_mul_f32 v[46:47], v[46:47], v[46:47]
	v_pk_mul_f32 v[42:43], v[42:43], v[42:43]
	v_pk_mul_f32 v[38:39], v[38:39], v[38:39]
	v_cvt_pk_bf16_f32 v188, v50, v46
	v_cvt_pk_bf16_f32 v189, v42, v38
	v_add_u32_e32 v3, 0x120000, v175
	global_store_dwordx2 v3, v[188:189], s[4:5] sc1
	v_cvt_pk_bf16_f32 v190, v51, v47
	v_cvt_pk_bf16_f32 v191, v43, v39
	v_add_u32_e32 v192, 0x122000, v175
	global_store_dwordx2 v192, v[190:191], s[4:5] sc1
	v_pk_mul_f32 v[52:53], v[52:53], v[186:187]
	v_pk_mul_f32 v[48:49], v[48:49], v[186:187]
	v_pk_mul_f32 v[44:45], v[44:45], v[186:187]
	v_pk_mul_f32 v[40:41], v[40:41], v[186:187]
	v_max_f32_e32 v52, 0, v52
	v_max_f32_e32 v53, 0, v53
	v_max_f32_e32 v48, 0, v48
	v_max_f32_e32 v49, 0, v49
	v_max_f32_e32 v44, 0, v44
	v_max_f32_e32 v45, 0, v45
	v_max_f32_e32 v40, 0, v40
	v_max_f32_e32 v41, 0, v41
	v_pk_mul_f32 v[52:53], v[52:53], v[52:53]
	v_pk_mul_f32 v[48:49], v[48:49], v[48:49]
	v_pk_mul_f32 v[44:45], v[44:45], v[44:45]
	v_pk_mul_f32 v[40:41], v[40:41], v[40:41]
	v_cvt_pk_bf16_f32 v194, v52, v48
	v_cvt_pk_bf16_f32 v195, v44, v40
	v_add_u32_e32 v193, 0x124000, v175
	global_store_dwordx2 v193, v[194:195], s[4:5] sc1
	v_cvt_pk_bf16_f32 v196, v53, v49
	v_cvt_pk_bf16_f32 v197, v45, v41
	v_add_u32_e32 v2, 0x126000, v175
	global_store_dwordx2 v2, v[196:197], s[4:5] sc1
	s_waitcnt lgkmcnt(1)
	v_mov_b32_dpp v184, v182 quad_perm:[0,0,0,0] row_mask:0xf bank_mask:0xf
	v_mov_b32_dpp v185, v182 quad_perm:[1,1,1,1] row_mask:0xf bank_mask:0xf
	v_mov_b32_dpp v186, v182 quad_perm:[2,2,2,2] row_mask:0xf bank_mask:0xf
	v_mov_b32_dpp v187, v182 quad_perm:[3,3,3,3] row_mask:0xf bank_mask:0xf
	v_pk_mul_f32 v[34:35], v[34:35], v[184:185]
	v_pk_mul_f32 v[30:31], v[30:31], v[184:185]
	v_pk_mul_f32 v[26:27], v[26:27], v[184:185]
	v_pk_mul_f32 v[22:23], v[22:23], v[184:185]
	v_max_f32_e32 v34, 0, v34
	v_max_f32_e32 v35, 0, v35
	v_max_f32_e32 v30, 0, v30
	v_max_f32_e32 v31, 0, v31
	v_max_f32_e32 v26, 0, v26
	v_max_f32_e32 v27, 0, v27
	v_max_f32_e32 v22, 0, v22
	v_max_f32_e32 v23, 0, v23
	v_pk_mul_f32 v[34:35], v[34:35], v[34:35]
	v_pk_mul_f32 v[30:31], v[30:31], v[30:31]
	v_pk_mul_f32 v[26:27], v[26:27], v[26:27]
	v_pk_mul_f32 v[22:23], v[22:23], v[22:23]
	v_cvt_pk_bf16_f32 v188, v34, v30
	v_cvt_pk_bf16_f32 v189, v26, v22
	v_add_u32_e32 v3, 0x140000, v175
	global_store_dwordx2 v3, v[188:189], s[4:5] sc1
	v_cvt_pk_bf16_f32 v190, v35, v31
	v_cvt_pk_bf16_f32 v191, v27, v23
	v_add_u32_e32 v192, 0x142000, v175
	global_store_dwordx2 v192, v[190:191], s[4:5] sc1
	v_pk_mul_f32 v[36:37], v[36:37], v[186:187]
	v_pk_mul_f32 v[32:33], v[32:33], v[186:187]
	v_pk_mul_f32 v[28:29], v[28:29], v[186:187]
	v_pk_mul_f32 v[24:25], v[24:25], v[186:187]
	v_max_f32_e32 v36, 0, v36
	v_max_f32_e32 v37, 0, v37
	v_max_f32_e32 v32, 0, v32
	v_max_f32_e32 v33, 0, v33
	v_max_f32_e32 v28, 0, v28
	v_max_f32_e32 v29, 0, v29
	v_max_f32_e32 v24, 0, v24
	v_max_f32_e32 v25, 0, v25
	v_pk_mul_f32 v[36:37], v[36:37], v[36:37]
	v_pk_mul_f32 v[32:33], v[32:33], v[32:33]
	v_pk_mul_f32 v[28:29], v[28:29], v[28:29]
	v_pk_mul_f32 v[24:25], v[24:25], v[24:25]
	v_cvt_pk_bf16_f32 v194, v36, v32
	v_cvt_pk_bf16_f32 v195, v28, v24
	v_add_u32_e32 v193, 0x144000, v175
	global_store_dwordx2 v193, v[194:195], s[4:5] sc1
	v_cvt_pk_bf16_f32 v196, v37, v33
	v_cvt_pk_bf16_f32 v197, v29, v25
	v_add_u32_e32 v2, 0x146000, v175
	global_store_dwordx2 v2, v[196:197], s[4:5] sc1
	s_waitcnt lgkmcnt(0)
	v_mov_b32_dpp v184, v183 quad_perm:[0,0,0,0] row_mask:0xf bank_mask:0xf
	v_mov_b32_dpp v185, v183 quad_perm:[1,1,1,1] row_mask:0xf bank_mask:0xf
	v_mov_b32_dpp v186, v183 quad_perm:[2,2,2,2] row_mask:0xf bank_mask:0xf
	v_mov_b32_dpp v187, v183 quad_perm:[3,3,3,3] row_mask:0xf bank_mask:0xf
	v_pk_mul_f32 v[18:19], v[18:19], v[184:185]
	v_pk_mul_f32 v[14:15], v[14:15], v[184:185]
	v_pk_mul_f32 v[10:11], v[10:11], v[184:185]
	v_pk_mul_f32 v[6:7], v[6:7], v[184:185]
	v_max_f32_e32 v18, 0, v18
	v_max_f32_e32 v19, 0, v19
	v_max_f32_e32 v14, 0, v14
	v_max_f32_e32 v15, 0, v15
	v_max_f32_e32 v10, 0, v10
	v_max_f32_e32 v11, 0, v11
	v_max_f32_e32 v6, 0, v6
	v_max_f32_e32 v7, 0, v7
	v_pk_mul_f32 v[18:19], v[18:19], v[18:19]
	v_pk_mul_f32 v[14:15], v[14:15], v[14:15]
	v_pk_mul_f32 v[10:11], v[10:11], v[10:11]
	v_pk_mul_f32 v[6:7], v[6:7], v[6:7]
	v_cvt_pk_bf16_f32 v188, v18, v14
	v_cvt_pk_bf16_f32 v189, v10, v6
	v_add_u32_e32 v3, 0x160000, v175
	global_store_dwordx2 v3, v[188:189], s[4:5] sc1
	v_cvt_pk_bf16_f32 v190, v19, v15
	v_cvt_pk_bf16_f32 v191, v11, v7
	v_add_u32_e32 v192, 0x162000, v175
	global_store_dwordx2 v192, v[190:191], s[4:5] sc1
	v_pk_mul_f32 v[20:21], v[20:21], v[186:187]
	v_pk_mul_f32 v[16:17], v[16:17], v[186:187]
	v_pk_mul_f32 v[12:13], v[12:13], v[186:187]
	v_pk_mul_f32 v[8:9], v[8:9], v[186:187]
	v_max_f32_e32 v20, 0, v20
	v_max_f32_e32 v21, 0, v21
	v_max_f32_e32 v16, 0, v16
	v_max_f32_e32 v17, 0, v17
	v_max_f32_e32 v12, 0, v12
	v_max_f32_e32 v13, 0, v13
	v_max_f32_e32 v8, 0, v8
	v_max_f32_e32 v9, 0, v9
	v_pk_mul_f32 v[20:21], v[20:21], v[20:21]
	v_pk_mul_f32 v[16:17], v[16:17], v[16:17]
	v_pk_mul_f32 v[12:13], v[12:13], v[12:13]
	v_pk_mul_f32 v[8:9], v[8:9], v[8:9]
	v_cvt_pk_bf16_f32 v194, v20, v16
	v_cvt_pk_bf16_f32 v195, v12, v8
	v_add_u32_e32 v193, 0x164000, v175
	global_store_dwordx2 v193, v[194:195], s[4:5] sc1
	v_cvt_pk_bf16_f32 v196, v21, v17
	v_cvt_pk_bf16_f32 v197, v13, v9
	v_add_u32_e32 v2, 0x166000, v175
	global_store_dwordx2 v2, v[196:197], s[4:5] sc1
	s_andn2_b64 vcc, exec, s[20:21]
	s_mov_b64 s[20:21], -1
	s_cbranch_vccnz .LBB0_936
	s_andn2_b64 vcc, exec, s[2:3]
	s_cbranch_vccnz .LBB0_935
	s_barrier
	s_branch .LBB0_935
